# B2 + non-leader workgroups issue their acquire buffer_inv at arrival (while waiting for release); XCD leaders keep the post-release invalidate
# baseline (speedup 1.0000x reference)
; __device__ __forceinline__ unsigned xb_ld(unsigned* p)              { return __hip_atomic_load(p, __ATOMIC_RELAXED, __HIP_MEMORY_SCOPE_AGENT); }
; __device__ __forceinline__ unsigned xb_add(unsigned* p, unsigned v) { return __hip_atomic_fetch_add(p, v, __ATOMIC_RELAXED, __HIP_MEMORY_SCOPE_AGENT); }
; #define XB_SPIN(cond, bar) do { unsigned _sp = 0; while (cond) { __builtin_amdgcn_s_sleep(1); \
;     if ((++_sp & 255u) == 0u) { if (xb_ld(&(bar)[XB_TMO])) break; if (_sp > XB_SPIN_CAP) { atomicAdd(&(bar)[XB_TMO], 1u); break; } } } } while (0)
; __device__ __forceinline__ void xcd_barrier(const XcdBarrier& b, int tid) {
;     ...
;         unsigned nloc = b.st[0], nx = b.st[1];
;         if (nloc == 0u) { xcd_barrier_complete(bar, b.x, nloc, nx); b.st[0] = nloc; b.st[1] = nx; }
;         const unsigned old = xb_add(&bar[XB_XSUB(b.x)], 1u);
;         const unsigned gen = old / nloc;
;         if (old + 1u == (gen + 1u) * nloc) {
;             __builtin_amdgcn_fence(__ATOMIC_RELEASE, "agent");
;             asm volatile("s_waitcnt vmcnt(0)" ::: "memory");
;             const unsigned og = xb_add(&bar[XB_TOP], 1u);
;             const unsigned tg = og / nx;
;             if (og + 1u == (tg + 1u) * nx) xb_add(&bar[XB_TOPGEN], 1u);
;             else XB_SPIN(xb_ld(&bar[XB_TOPGEN]) == tg, bar);
;             __builtin_amdgcn_fence(__ATOMIC_ACQUIRE, "agent");
;             xb_add(&bar[XB_XGEN(b.x)], 1u);
;             asm volatile("s_waitcnt vmcnt(0)" ::: "memory");
;         } else {
;             XB_SPIN(xb_ld(&bar[XB_XGEN(b.x)]) == gen, bar);
;             __builtin_amdgcn_fence(__ATOMIC_ACQUIRE, "agent");
;             asm volatile("s_waitcnt vmcnt(0)" ::: "memory");
.LBB0_62:
	s_lshl_b32 s2, s26, 8
	s_add_u32 s2, s16, s2
	s_addc_u32 s3, s17, 0
	v_mov_b32_e32 v1, 0x1000
	v_mov_b32_e32 v3, 1
	global_atomic_add v3, v1, v3, s[2:3] offset:1024 sc0
	v_cvt_f32_u32_e32 v1, v2
	v_sub_u32_e32 v4, 0, v2
	v_rcp_iflag_f32_e32 v1, v1
	s_nop 0
	v_mul_f32_e32 v1, 0x4f7ffffe, v1
	v_cvt_u32_f32_e32 v1, v1
	v_mul_lo_u32 v4, v4, v1
	v_mul_hi_u32 v4, v1, v4
	v_add_u32_e32 v1, v1, v4
	s_waitcnt vmcnt(0)
	v_mul_hi_u32 v1, v3, v1
	v_mul_lo_u32 v4, v1, v2
	v_sub_u32_e32 v4, v3, v4
	v_add_u32_e32 v5, 1, v1
	v_cmp_ge_u32_e32 vcc, v4, v2
	v_add_u32_e32 v3, 1, v3
	s_nop 0
	v_cndmask_b32_e32 v1, v1, v5, vcc
	v_sub_u32_e32 v5, v4, v2
	v_cndmask_b32_e32 v4, v4, v5, vcc
	v_add_u32_e32 v5, 1, v1
	v_cmp_ge_u32_e32 vcc, v4, v2
	s_nop 1
	v_cndmask_b32_e32 v1, v1, v5, vcc
	v_mul_lo_u32 v4, v2, v1
	v_add_u32_e32 v2, v4, v2
	v_cmp_ne_u32_e32 vcc, v3, v2
	s_and_saveexec_b64 s[4:5], vcc
	s_xor_b64 s[4:5], exec, s[4:5]
	s_cbranch_execz .LBB0_76
	buffer_inv sc1
	s_waitcnt lgkmcnt(0)
	v_mov_b32_e32 v0, 0x2000
	global_load_dword v0, v0, s[2:3] offset:1024 sc1
	s_add_u32 s10, s2, 0x2400
	s_addc_u32 s11, s3, 0
	s_waitcnt vmcnt(0)
	v_cmp_eq_u32_e32 vcc, v0, v1
	s_and_saveexec_b64 s[6:7], vcc
	s_cbranch_execz .LBB0_75
	s_add_u32 s8, s82, 0x4200
	s_addc_u32 s9, s83, 0
	s_mov_b32 s24, 1
	s_mov_b64 s[12:13], 0
	v_mov_b32_e32 v0, 0
	s_branch .LBB0_66

; __device__ __forceinline__ unsigned xb_ld(unsigned* p)              { return __hip_atomic_load(p, __ATOMIC_RELAXED, __HIP_MEMORY_SCOPE_AGENT); }
; __device__ __forceinline__ unsigned xb_add(unsigned* p, unsigned v) { return __hip_atomic_fetch_add(p, v, __ATOMIC_RELAXED, __HIP_MEMORY_SCOPE_AGENT); }
; #define XB_SPIN(cond, bar) do { unsigned _sp = 0; while (cond) { __builtin_amdgcn_s_sleep(1); \
;     if ((++_sp & 255u) == 0u) { if (xb_ld(&(bar)[XB_TMO])) break; if (_sp > XB_SPIN_CAP) { atomicAdd(&(bar)[XB_TMO], 1u); break; } } } } while (0)
; __device__ __forceinline__ void xcd_barrier(const XcdBarrier& b, int tid) {
;     ...
;         unsigned nloc = b.st[0], nx = b.st[1];
;         if (nloc == 0u) { xcd_barrier_complete(bar, b.x, nloc, nx); b.st[0] = nloc; b.st[1] = nx; }
;         const unsigned old = xb_add(&bar[XB_XSUB(b.x)], 1u);
;         const unsigned gen = old / nloc;
;         if (old + 1u == (gen + 1u) * nloc) {
;             __builtin_amdgcn_fence(__ATOMIC_RELEASE, "agent");
;             asm volatile("s_waitcnt vmcnt(0)" ::: "memory");
;             const unsigned og = xb_add(&bar[XB_TOP], 1u);
;             const unsigned tg = og / nx;
;             if (og + 1u == (tg + 1u) * nx) xb_add(&bar[XB_TOPGEN], 1u);
;             else XB_SPIN(xb_ld(&bar[XB_TOPGEN]) == tg, bar);
;             __builtin_amdgcn_fence(__ATOMIC_ACQUIRE, "agent");
;             xb_add(&bar[XB_XGEN(b.x)], 1u);
;             asm volatile("s_waitcnt vmcnt(0)" ::: "memory");
;         } else {
;             XB_SPIN(xb_ld(&bar[XB_XGEN(b.x)]) == gen, bar);
;             __builtin_amdgcn_fence(__ATOMIC_ACQUIRE, "agent");
;             asm volatile("s_waitcnt vmcnt(0)" ::: "memory");
.LBB0_176:
	v_readlane_b32 s2, v254, 7
	v_readlane_b32 s3, v254, 8
	v_cvt_f32_u32_e32 v1, v2
	v_sub_u32_e32 v4, 0, v2
	v_rcp_iflag_f32_e32 v1, v1
	s_nop 1
	global_atomic_add v3, v161, v239, s[2:3] sc0
	v_mul_f32_e32 v1, 0x4f7ffffe, v1
	v_cvt_u32_f32_e32 v1, v1
	v_mul_lo_u32 v4, v4, v1
	v_mul_hi_u32 v4, v1, v4
	v_add_u32_e32 v1, v1, v4
	s_waitcnt vmcnt(0)
	v_mul_hi_u32 v1, v3, v1
	v_mul_lo_u32 v4, v1, v2
	v_sub_u32_e32 v4, v3, v4
	v_add_u32_e32 v5, 1, v1
	v_cmp_ge_u32_e32 vcc, v4, v2
	v_add_u32_e32 v3, 1, v3
	s_nop 0
	v_cndmask_b32_e32 v1, v1, v5, vcc
	v_sub_u32_e32 v5, v4, v2
	v_cndmask_b32_e32 v4, v4, v5, vcc
	v_add_u32_e32 v5, 1, v1
	v_cmp_ge_u32_e32 vcc, v4, v2
	s_nop 1
	v_cndmask_b32_e32 v1, v1, v5, vcc
	v_mul_lo_u32 v4, v2, v1
	v_add_u32_e32 v2, v4, v2
	v_cmp_ne_u32_e32 vcc, v3, v2
	s_and_saveexec_b64 s[2:3], vcc
	s_xor_b64 s[2:3], exec, s[2:3]
	s_cbranch_execz .LBB0_190
	buffer_inv sc1
	v_readlane_b32 s4, v254, 9
	v_readlane_b32 s5, v254, 10
	s_waitcnt lgkmcnt(0)
	s_nop 3
	global_load_dword v0, v161, s[4:5] sc1
	s_waitcnt vmcnt(0)
	v_cmp_eq_u32_e32 vcc, v0, v1
	s_and_saveexec_b64 s[4:5], vcc
	s_cbranch_execz .LBB0_189
	s_mov_b32 s18, 1
	s_mov_b64 s[6:7], 0
	s_branch .LBB0_180

; __device__ __forceinline__ unsigned xb_ld(unsigned* p)              { return __hip_atomic_load(p, __ATOMIC_RELAXED, __HIP_MEMORY_SCOPE_AGENT); }
; __device__ __forceinline__ unsigned xb_add(unsigned* p, unsigned v) { return __hip_atomic_fetch_add(p, v, __ATOMIC_RELAXED, __HIP_MEMORY_SCOPE_AGENT); }
; #define XB_SPIN(cond, bar) do { unsigned _sp = 0; while (cond) { __builtin_amdgcn_s_sleep(1); \
;     if ((++_sp & 255u) == 0u) { if (xb_ld(&(bar)[XB_TMO])) break; if (_sp > XB_SPIN_CAP) { atomicAdd(&(bar)[XB_TMO], 1u); break; } } } } while (0)
; __device__ __forceinline__ void xcd_barrier(const XcdBarrier& b, int tid) {
;     ...
;         unsigned nloc = b.st[0], nx = b.st[1];
;         if (nloc == 0u) { xcd_barrier_complete(bar, b.x, nloc, nx); b.st[0] = nloc; b.st[1] = nx; }
;         const unsigned old = xb_add(&bar[XB_XSUB(b.x)], 1u);
;         const unsigned gen = old / nloc;
;         if (old + 1u == (gen + 1u) * nloc) {
;             __builtin_amdgcn_fence(__ATOMIC_RELEASE, "agent");
;             asm volatile("s_waitcnt vmcnt(0)" ::: "memory");
;             const unsigned og = xb_add(&bar[XB_TOP], 1u);
;             const unsigned tg = og / nx;
;             if (og + 1u == (tg + 1u) * nx) xb_add(&bar[XB_TOPGEN], 1u);
;             else XB_SPIN(xb_ld(&bar[XB_TOPGEN]) == tg, bar);
;             __builtin_amdgcn_fence(__ATOMIC_ACQUIRE, "agent");
;             xb_add(&bar[XB_XGEN(b.x)], 1u);
;             asm volatile("s_waitcnt vmcnt(0)" ::: "memory");
;         } else {
;             XB_SPIN(xb_ld(&bar[XB_XGEN(b.x)]) == gen, bar);
;             __builtin_amdgcn_fence(__ATOMIC_ACQUIRE, "agent");
;             asm volatile("s_waitcnt vmcnt(0)" ::: "memory");
.LBB0_1502:
	v_readlane_b32 s0, v254, 7
	v_readlane_b32 s1, v254, 8
	v_cvt_f32_u32_e32 v1, v2
	v_sub_u32_e32 v4, 0, v2
	v_rcp_iflag_f32_e32 v1, v1
	s_nop 1
	global_atomic_add v3, v161, v239, s[0:1] sc0
	v_mul_f32_e32 v1, 0x4f7ffffe, v1
	v_cvt_u32_f32_e32 v1, v1
	v_mul_lo_u32 v4, v4, v1
	v_mul_hi_u32 v4, v1, v4
	v_add_u32_e32 v1, v1, v4
	s_waitcnt vmcnt(0)
	v_mul_hi_u32 v1, v3, v1
	v_mul_lo_u32 v4, v1, v2
	v_sub_u32_e32 v4, v3, v4
	v_add_u32_e32 v5, 1, v1
	v_cmp_ge_u32_e32 vcc, v4, v2
	v_add_u32_e32 v3, 1, v3
	s_nop 0
	v_cndmask_b32_e32 v1, v1, v5, vcc
	v_sub_u32_e32 v5, v4, v2
	v_cndmask_b32_e32 v4, v4, v5, vcc
	v_add_u32_e32 v5, 1, v1
	v_cmp_ge_u32_e32 vcc, v4, v2
	s_nop 1
	v_cndmask_b32_e32 v1, v1, v5, vcc
	v_mul_lo_u32 v4, v2, v1
	v_add_u32_e32 v2, v4, v2
	v_cmp_ne_u32_e32 vcc, v3, v2
	s_and_saveexec_b64 s[0:1], vcc
	s_xor_b64 s[4:5], exec, s[0:1]
	s_cbranch_execz .LBB0_1516
	buffer_inv sc1
	v_readlane_b32 s0, v254, 9
	v_readlane_b32 s1, v254, 10
	s_waitcnt lgkmcnt(0)
	s_nop 3
	global_load_dword v0, v161, s[0:1] sc1
	s_waitcnt vmcnt(0)
	v_cmp_eq_u32_e32 vcc, v0, v1
	s_and_saveexec_b64 s[6:7], vcc
	s_cbranch_execz .LBB0_1515
	s_mov_b32 s0, 1
	s_mov_b64 s[8:9], 0
	s_branch .LBB0_1506

; __device__ __forceinline__ unsigned xb_ld(unsigned* p)              { return __hip_atomic_load(p, __ATOMIC_RELAXED, __HIP_MEMORY_SCOPE_AGENT); }
; __device__ __forceinline__ unsigned xb_add(unsigned* p, unsigned v) { return __hip_atomic_fetch_add(p, v, __ATOMIC_RELAXED, __HIP_MEMORY_SCOPE_AGENT); }
; #define XB_SPIN(cond, bar) do { unsigned _sp = 0; while (cond) { __builtin_amdgcn_s_sleep(1); \
;     if ((++_sp & 255u) == 0u) { if (xb_ld(&(bar)[XB_TMO])) break; if (_sp > XB_SPIN_CAP) { atomicAdd(&(bar)[XB_TMO], 1u); break; } } } } while (0)
; __device__ __forceinline__ void xcd_barrier(const XcdBarrier& b, int tid) {
;     ...
;         unsigned nloc = b.st[0], nx = b.st[1];
;         if (nloc == 0u) { xcd_barrier_complete(bar, b.x, nloc, nx); b.st[0] = nloc; b.st[1] = nx; }
;         const unsigned old = xb_add(&bar[XB_XSUB(b.x)], 1u);
;         const unsigned gen = old / nloc;
;         if (old + 1u == (gen + 1u) * nloc) {
;             __builtin_amdgcn_fence(__ATOMIC_RELEASE, "agent");
;             asm volatile("s_waitcnt vmcnt(0)" ::: "memory");
;             const unsigned og = xb_add(&bar[XB_TOP], 1u);
;             const unsigned tg = og / nx;
;             if (og + 1u == (tg + 1u) * nx) xb_add(&bar[XB_TOPGEN], 1u);
;             else XB_SPIN(xb_ld(&bar[XB_TOPGEN]) == tg, bar);
;             __builtin_amdgcn_fence(__ATOMIC_ACQUIRE, "agent");
;             xb_add(&bar[XB_XGEN(b.x)], 1u);
;             asm volatile("s_waitcnt vmcnt(0)" ::: "memory");
;         } else {
;             XB_SPIN(xb_ld(&bar[XB_XGEN(b.x)]) == gen, bar);
;             __builtin_amdgcn_fence(__ATOMIC_ACQUIRE, "agent");
;             asm volatile("s_waitcnt vmcnt(0)" ::: "memory");
.LBB0_1826:
	v_readlane_b32 s2, v254, 7
	v_mov_b32_e32 v3, 0
	v_mov_b32_e32 v1, 1
	v_readlane_b32 s3, v254, 8
	v_sub_u32_e32 v5, 0, v2
	s_nop 3
	global_atomic_add v4, v3, v1, s[2:3] sc0
	v_cvt_f32_u32_e32 v1, v2
	v_rcp_iflag_f32_e32 v1, v1
	s_nop 0
	v_mul_f32_e32 v1, 0x4f7ffffe, v1
	v_cvt_u32_f32_e32 v1, v1
	v_mul_lo_u32 v5, v5, v1
	v_mul_hi_u32 v5, v1, v5
	v_add_u32_e32 v1, v1, v5
	s_waitcnt vmcnt(0)
	v_mul_hi_u32 v1, v4, v1
	v_mul_lo_u32 v5, v1, v2
	v_sub_u32_e32 v5, v4, v5
	v_add_u32_e32 v6, 1, v1
	v_cmp_ge_u32_e32 vcc, v5, v2
	v_add_u32_e32 v4, 1, v4
	s_nop 0
	v_cndmask_b32_e32 v1, v1, v6, vcc
	v_sub_u32_e32 v6, v5, v2
	v_cndmask_b32_e32 v5, v5, v6, vcc
	v_add_u32_e32 v6, 1, v1
	v_cmp_ge_u32_e32 vcc, v5, v2
	s_nop 1
	v_cndmask_b32_e32 v1, v1, v6, vcc
	v_mul_lo_u32 v5, v2, v1
	v_add_u32_e32 v2, v5, v2
	v_cmp_ne_u32_e32 vcc, v4, v2
	s_and_saveexec_b64 s[2:3], vcc
	s_xor_b64 s[2:3], exec, s[2:3]
	s_cbranch_execz .LBB0_1840
	buffer_inv sc1
	v_readlane_b32 s4, v254, 9
	v_readlane_b32 s5, v254, 10
	s_waitcnt lgkmcnt(0)
	s_nop 3
	global_load_dword v0, v3, s[4:5] sc1
	s_waitcnt vmcnt(0)
	v_cmp_eq_u32_e32 vcc, v0, v1
	s_and_saveexec_b64 s[4:5], vcc
	s_cbranch_execz .LBB0_1839
	s_mov_b32 s16, 1
	s_mov_b64 s[6:7], 0
	v_mov_b32_e32 v0, 0
	s_branch .LBB0_1830
